# MLA task order head-major and XCD-local: XCD x works on batch x, each round covers 4 heads of all batches (matches the order the Q/KV columns were produced)
# baseline (speedup 1.0000x reference)
; __device__ __forceinline__ int otid() { int t = threadIdx.x; asm volatile("" : "+v"(t)); return t; }
; template <int MODE>
; __device__ __forceinline__ void attn_body(const Job J, char* lds) {
;     ...
;   const int tid = otid(), wid = tid >> 6, lane = tid & 63, r32 = lane & 31, hi = lane >> 5;
;   char* V_lds = lds; char* K_lds = lds + 2 * SHM_V;
;   float* wsf = (float*)(lds + 2 * SHM_V + 2 * SHM_K) + wid * 64; float* li_l = wsf; float* al_l = wsf + 32;
;   const float* tab = (const float*)(lds + 2 * SHM_V + 2 * SHM_K + NW * 256) + 64;
;   constexpr int NQR = (MODE == 2) ? 4 : 8;
;   float m_reg = -1e30f, l_reg = 0; f32x16 o[4] = {}; bf16x8 qr[NQR];
;   const bf16_t* Qw = J.Qb + (size_t)(wid * QBLK + r32) * J.ldq + hi * 8;
;   char* ql = lds + 2 * SHM_V + 2 * SHM_K + NW * 256 + (wid * 8 * 64 + lane) * 16;
; #pragma unroll
;   for (int d0 = 0; d0 < NQR; ++d0) qr[d0] = *reinterpret_cast<const bf16x8*>(Qw + d0 * 16);
;   if constexpr (MODE == 2) {
; #pragma unroll
;     for (int d0 = 4; d0 < 8; ++d0) *reinterpret_cast<bf16x8*>(ql + (d0 - 4) * 1024) = *reinterpret_cast<const bf16x8*>(Qw + d0 * 16);
;     const int tok = J.tok0 + wid * QBLK + r32; const int prow = tok >> 6, pcol = tok & 63;
; #pragma unroll
;     for (int ax = 0; ax < 2; ++ax) {
;       const float* cs = J.rope + (size_t)((ax == 0 ? prow : pcol) * 16 + hi * 8) * 2;
;       bf16x8 x1 = *reinterpret_cast<const bf16x8*>(Qw + (8 + 2 * ax) * 16), x2 = *reinterpret_cast<const bf16x8*>(Qw + (9 + 2 * ax) * 16); u32x4 w1, w2;
; #pragma unroll
;       for (int i = 0; i < 4; ++i) {
;         const f32x4 t = *(const f32x4*)(cs + 4 * i);
; __device__ __forceinline__ void mla_task(const Params& p, int task, char* shm) {
;   const int qb = task & 7, h = (task >> 3) & 15, b = task >> 7;
;   const bf16_t* Q = (const bf16_t*)(p.ws + OFF_Q); const bf16_t* KV = (const bf16_t*)(p.ws + OFF_KV); bf16_t* ATT = (bf16_t*)(p.ws + OFF_H);
;   __syncthreads();
;   att::Job J;
;   J.Qb = Q + (size_t)(b * 2048 + qb * 256) * 3072 + h * 192; J.ldq = 3072;
;   J.Kb = KV + h * 256; J.Vb = KV + h * 256 + 128; J.ldk = 4096; J.Pe = (const bf16_t*)(p.ws + OFF_KPE);
;   J.Ob = ATT + (size_t)(b * 2048 + qb * 256) * DM + h * 128; J.ldo = DM;
;   J.NT = 36; J.nA = 32; J.rowA = b * 2048; J.rowB = ML + b * 256; J.qb4 = 0; J.lo = 0; J.nwin = 0;
;   J.rope = (const float*)(p.ws + OFF_ROPE); J.tok0 = qb * 256;
;   att::attn_body<2>(J, shm);
.LBB0_1392:
	s_bfe_u32 s72, s71, 0x30003
	s_bfe_u32 s6, s71, 0x20006
	s_lshl_b32 s6, s6, 3
	s_or_b32 s72, s72, s6
	s_and_b32 s6, s71, 7
	s_lshl_b32 s6, s6, 7
	s_or_b32 s72, s72, s6
	s_lshr_b32 s6, s71, 3
	s_and_b32 s6, s6, 0x60
	s_or_b32 s72, s72, s6
	s_ashr_i32 s6, s72, 7
	s_lshl_b32 s7, s72, 8
	s_lshl_b32 s73, s6, 11
	s_and_b32 s7, s7, 0x700
	s_or_b32 s36, s73, s7
	s_bfe_u32 s72, s72, 0x40003
	s_ashr_i32 s37, s36, 31
	s_mul_i32 s9, s36, 0x1800
	s_mul_hi_i32 s8, s36, 0x1800
	s_add_u32 s9, s0, s9
	v_mov_b32_e32 v119, v170
	s_barrier
	s_addc_u32 s38, s1, s8
	s_mul_i32 s8, s72, 0x180
	s_add_u32 s8, s9, s8
	v_ashrrev_i32_e32 v32, 6, v119
	v_and_b32_e32 v138, 31, v119
	v_lshlrev_b32_e32 v118, 5, v32
	v_or_b32_e32 v16, s7, v138
	s_addc_u32 s9, s38, 0
	v_bfe_u32 v137, v119, 5, 1
	v_add_u32_e32 v34, v16, v118
	v_or_b32_e32 v2, v118, v138
	v_mov_b64_e32 v[0:1], s[8:9]
	v_lshlrev_b32_e32 v33, 3, v137
	v_ashrrev_i32_e32 v16, 2, v34
	v_mad_i64_i32 v[0:1], s[8:9], v2, s40, v[0:1]
	v_lshlrev_b32_e32 v116, 4, v137
	v_and_or_b32 v24, v16, -16, v33
	v_lshl_add_u64 v[28:29], v[0:1], 0, v[116:117]
	v_ashrrev_i32_e32 v25, 31, v24
	global_load_dwordx4 v[0:3], v[28:29], off offset:128
	global_load_dwordx4 v[4:7], v[28:29], off offset:160
	global_load_dwordx4 v[8:11], v[28:29], off offset:192
	global_load_dwordx4 v[12:15], v[28:29], off offset:224
	global_load_dwordx4 v[16:19], v[28:29], off offset:256
	global_load_dwordx4 v[20:23], v[28:29], off offset:288
	v_lshl_add_u64 v[30:31], v[24:25], 3, s[30:31]
	global_load_dwordx4 v[24:27], v[30:31], off
	v_and_b32_e32 v120, 63, v119
	v_lshl_add_u32 v32, v32, 13, s43
	v_lshlrev_b32_e32 v121, 4, v120
	v_add_u32_e32 v142, v32, v121
	global_load_dwordx4 v[108:111], v[28:29], off
	global_load_dwordx4 v[104:107], v[28:29], off offset:32
	global_load_dwordx4 v[100:103], v[28:29], off offset:64
	global_load_dwordx4 v[96:99], v[28:29], off offset:96
	global_load_dwordx4 v[224:227], v[30:31], off offset:16
	global_load_dwordx4 v[228:231], v[30:31], off offset:32
	global_load_dwordx4 v[232:235], v[30:31], off offset:48
	v_ashrrev_i32_e32 v144, 3, v119
	v_ashrrev_i32_e32 v143, 4, v119
	s_lshl_b32 s7, s72, 9
	v_add_u32_e32 v145, 32, v143
	s_add_u32 s8, s2, s7
	v_mov_b32_e32 v115, v117
	s_addc_u32 s9, s3, 0
	v_mov_b32_e32 v113, v117
	v_lshlrev_b32_e32 v32, 1, v143
	v_mul_lo_u32 v35, v143, s41
	v_lshlrev_b32_e32 v37, 3, v144
	v_mul_lo_u32 v36, v144, s41
	v_mad_u32_u24 v122, v138, s41, 0
	v_add_u32_e32 v35, 0, v35
	v_and_b32_e32 v37, 0x70, v37
	v_add_u32_e32 v36, 0, v36
	v_add_u32_e32 v38, 0x3000, v35
	s_lshl_b32 s74, s6, 8
	s_addk_i32 s74, 0x4000
	s_cmp_lg_u32 0, -1
	s_cselect_b32 s38, 0, 0
	v_and_b32_e32 v123, 0x3fffffc0, v119
	v_lshlrev_b32_e32 v125, 1, v119
	v_and_b32_e32 v126, 0xc0, v121
	v_add_u32_e32 v178, 0xe000, v122
	v_and_b32_e32 v125, 32, v125
	s_mov_b32 s75, 2
	s_waitcnt vmcnt(13)
	ds_write_b128 v142, v[0:3]
	s_waitcnt vmcnt(12)
	ds_write_b128 v142, v[4:7] offset:1024
	s_waitcnt vmcnt(11)
	ds_write_b128 v142, v[8:11] offset:2048
	s_waitcnt vmcnt(10)
	ds_write_b128 v142, v[12:15] offset:3072
	s_waitcnt vmcnt(9)
	v_lshlrev_b32_e32 v1, 16, v16
	s_waitcnt vmcnt(8)
	v_lshlrev_b32_e32 v0, 16, v20
	v_and_b32_e32 v3, 0xffff0000, v16
	v_and_b32_e32 v2, 0xffff0000, v20
	s_waitcnt vmcnt(7)
	v_pk_mul_f32 v[4:5], v[24:25], v[0:1] op_sel:[0,1] op_sel_hi:[1,0]
	v_pk_mul_f32 v[0:1], v[24:25], v[0:1]
	v_pk_mul_f32 v[6:7], v[26:27], v[2:3] op_sel:[0,1] op_sel_hi:[1,0]
	v_pk_mul_f32 v[2:3], v[26:27], v[2:3]
	v_sub_f32_e32 v4, v4, v5
	v_add_f32_e32 v1, v1, v0
	v_sub_f32_e32 v0, v6, v7
	v_add_f32_e32 v2, v3, v2
	v_cvt_pk_bf16_f32 v0, v4, v0
	v_cvt_pk_bf16_f32 v4, v1, v2
	s_nop 0
	v_lshlrev_b32_e32 v3, 16, v17
	v_lshlrev_b32_e32 v2, 16, v21
	v_and_b32_e32 v11, 0xffff0000, v17
	v_and_b32_e32 v10, 0xffff0000, v21
	v_and_b32_e32 v15, 0xffff0000, v19
	v_and_b32_e32 v14, 0xffff0000, v23
	s_waitcnt vmcnt(2)
	v_pk_mul_f32 v[12:13], v[224:225], v[2:3] op_sel:[0,1] op_sel_hi:[1,0]
	v_pk_mul_f32 v[2:3], v[224:225], v[2:3]
	v_pk_mul_f32 v[6:7], v[226:227], v[10:11] op_sel:[0,1] op_sel_hi:[1,0]
	v_pk_mul_f32 v[8:9], v[226:227], v[10:11]
	v_sub_f32_e32 v1, v12, v13
	v_add_f32_e32 v5, v9, v8
	v_add_f32_e32 v2, v3, v2
	v_sub_f32_e32 v3, v6, v7
	v_cvt_pk_bf16_f32 v1, v1, v3
	v_cvt_pk_bf16_f32 v5, v2, v5
	s_nop 0
	v_lshlrev_b32_e32 v3, 16, v18
	v_lshlrev_b32_e32 v2, 16, v22
	v_and_b32_e32 v11, 0xffff0000, v18
	v_and_b32_e32 v10, 0xffff0000, v22
	v_lshlrev_b32_e32 v18, 4, v34
	v_and_b32_e32 v34, 3, v143
	s_waitcnt vmcnt(1)
	v_pk_mul_f32 v[12:13], v[228:229], v[2:3] op_sel:[0,1] op_sel_hi:[1,0]
	v_pk_mul_f32 v[2:3], v[228:229], v[2:3]
	v_pk_mul_f32 v[6:7], v[230:231], v[10:11] op_sel:[0,1] op_sel_hi:[1,0]
	v_pk_mul_f32 v[8:9], v[230:231], v[10:11]
	v_sub_f32_e32 v10, v12, v13
	v_add_f32_e32 v3, v3, v2
	v_sub_f32_e32 v2, v6, v7
	v_add_f32_e32 v6, v9, v8
	v_cvt_pk_bf16_f32 v2, v10, v2
	v_cvt_pk_bf16_f32 v6, v3, v6
	s_nop 0
	v_lshlrev_b32_e32 v13, 16, v19
	v_lshlrev_b32_e32 v12, 16, v23
	v_lshlrev_b32_e32 v30, 3, v119
	v_lshlrev_b32_e32 v31, 4, v119
	v_and_b32_e32 v114, 0x70, v31
	v_bitop3_b32 v146, v116, v30, s47 bitop3:0x78
	v_bitop3_b32 v37, v114, v37, s46 bitop3:0x36
	v_and_b32_e32 v31, 0x70, v30
	v_add_u32_e32 v147, v122, v146
	v_add_u32_e32 v150, v36, v37
	v_bitop3_b32 v158, v116, v31, 32 bitop3:0x36
	v_add_u32_e32 v153, v122, v158
	v_bitop3_b32 v161, v116, v31, 64 bitop3:0x36
	v_add_u32_e32 v154, v122, v161
	v_bitop3_b32 v164, v116, v31, s49 bitop3:0x36
	v_add_u32_e32 v155, v122, v164
	v_bitop3_b32 v167, v116, v31, s50 bitop3:0x36
	v_add_u32_e32 v156, v122, v167
	v_bitop3_b32 v169, v116, v31, s51 bitop3:0x36
	v_add_u32_e32 v160, v122, v169
	v_bitop3_b32 v172, v116, v31, s45 bitop3:0x36
	v_add_u32_e32 v159, v122, v172
	v_bitop3_b32 v173, v116, v31, s52 bitop3:0x36
	v_add_u32_e32 v162, v122, v173
	v_bitop3_b32 v174, v116, v31, s46 bitop3:0x36
	v_add_u32_e32 v163, v122, v174
	v_bitop3_b32 v175, v116, v31, s53 bitop3:0x36
	v_add_u32_e32 v166, v122, v175
	v_bitop3_b32 v176, v116, v31, s54 bitop3:0x36
	v_add_u32_e32 v165, v122, v176
	v_bitop3_b32 v177, v116, v31, s55 bitop3:0x36
	v_add_u32_e32 v168, v122, v177
	s_waitcnt vmcnt(0)
; __device__ __forceinline__ unsigned cvt_pk_bf16(float lo, float hi) { unsigned r; asm volatile("v_cvt_pk_bf16_f32 %0, %1, %2" : "=v"(r) : "v"(lo), "v"(hi)); return r; }
; __device__ __forceinline__ float bf2f(bf16_t b) { return __uint_as_float(((unsigned)b) << 16); }
; __device__ __forceinline__ int v_st(int k, int c) { const int kk = (k & ~0xC) | ((k & 4) << 1) | ((k & 8) >> 1); return ((kk >> 3) * 4 + (c >> 5)) * 512 + ((kk & 7) * 32 + (c & 31)) * 2; }
; __device__ __forceinline__ int v_rd_base(int lane) { return ((lane & 3) << 3) | (((lane >> 2) & 3) << 6) | (((lane >> 4) & 1) << 5) | (((lane >> 5) & 1) << 8); }
; #define SWAIT() asm volatile("s_waitcnt vmcnt(0)" ::: "memory")
; template <int MODE>
; __device__ __forceinline__ void attn_body(const Job J, char* lds) {
;     ...
; #pragma unroll
;     for (int ax = 0; ax < 2; ++ax) {
;       const float* cs = J.rope + (size_t)((ax == 0 ? prow : pcol) * 16 + hi * 8) * 2;
;       bf16x8 x1 = *reinterpret_cast<const bf16x8*>(Qw + (8 + 2 * ax) * 16), x2 = *reinterpret_cast<const bf16x8*>(Qw + (9 + 2 * ax) * 16); u32x4 w1, w2;
; #pragma unroll
;       for (int i = 0; i < 4; ++i) {
;         const f32x4 t = *(const f32x4*)(cs + 4 * i);
;         const float a0 = bf2f((bf16_t)x1[2 * i]), a1 = bf2f((bf16_t)x1[2 * i + 1]), b0 = bf2f((bf16_t)x2[2 * i]), b1 = bf2f((bf16_t)x2[2 * i + 1]);
;         w1[i] = cvt_pk_bf16(a0 * t[0] - b0 * t[1], a1 * t[2] - b1 * t[3]);
;         w2[i] = cvt_pk_bf16(a0 * t[1] + b0 * t[0], a1 * t[3] + b1 * t[2]);
;       }
;       *reinterpret_cast<u32x4*>(ql + (4 + 2 * ax) * 1024) = w1; *reinterpret_cast<u32x4*>(ql + (5 + 2 * ax) * 1024) = w2;
;     }
;   }
;   const int sr = tid >> 4, sc = (tid & 15) * 8, vst0 = v_st(sr, sc), vst1 = v_st(32 + sr, sc);
;   const int pr = tid >> 3, pc = (tid & 7) * 8;
;   const int vb0 = (int)(uintptr_t)V_lds + v_rd_base(lane);
;   bf16x8 vs0, vs1, ks0, ks1, kp;
;   const int rq = J.qb4 + (wid >> 1), qc = (wid & 1) * 32 + r32;
;   const int rs = min(max(rq - 4, 0), 24), cs_ = min(max(qc - 8, 0), 48);
;     ...
;   SLOAD(0); SWAIT(); SWRITE(0); __syncthreads();
	v_pk_mul_f32 v[16:17], v[232:233], v[12:13] op_sel:[0,1] op_sel_hi:[1,0]
	v_pk_mul_f32 v[8:9], v[232:233], v[12:13]
	v_pk_mul_f32 v[12:13], v[234:235], v[14:15] op_sel:[0,1] op_sel_hi:[1,0]
	v_pk_mul_f32 v[10:11], v[234:235], v[14:15]
	v_sub_f32_e32 v3, v16, v17
	v_add_f32_e32 v7, v9, v8
	v_sub_f32_e32 v8, v12, v13
	v_add_f32_e32 v9, v11, v10
	v_and_or_b32 v16, v18, s44, v33
	v_cvt_pk_bf16_f32 v3, v3, v8
	v_cvt_pk_bf16_f32 v7, v7, v9
	global_load_dwordx4 v[8:11], v[28:29], off offset:320
	global_load_dwordx4 v[12:15], v[28:29], off offset:352
	v_lshlrev_b32_e32 v20, 3, v16
	global_load_dwordx4 v[16:19], v20, s[30:31]
	global_load_dwordx4 v[236:239], v20, s[30:31] offset:16
	global_load_dwordx4 v[240:243], v20, s[30:31] offset:32
	global_load_dwordx4 v[244:247], v20, s[30:31] offset:48
	ds_write_b128 v142, v[0:3] offset:4096
	ds_write_b128 v142, v[4:7] offset:5120
	v_lshrrev_b32_e32 v33, 1, v143
	s_waitcnt vmcnt(5)
	v_lshlrev_b32_e32 v1, 16, v8
	s_waitcnt vmcnt(4)
	v_lshlrev_b32_e32 v0, 16, v12
	v_and_b32_e32 v3, 0xffff0000, v8
	v_and_b32_e32 v2, 0xffff0000, v12
	s_waitcnt vmcnt(3)
	v_pk_mul_f32 v[4:5], v[16:17], v[0:1] op_sel:[0,1] op_sel_hi:[1,0]
	v_pk_mul_f32 v[0:1], v[16:17], v[0:1]
	v_pk_mul_f32 v[6:7], v[18:19], v[2:3] op_sel:[0,1] op_sel_hi:[1,0]
	v_pk_mul_f32 v[2:3], v[18:19], v[2:3]
	v_sub_f32_e32 v4, v4, v5
	v_add_f32_e32 v0, v1, v0
	v_sub_f32_e32 v1, v6, v7
	v_add_f32_e32 v2, v3, v2
	v_cvt_pk_bf16_f32 v4, v4, v1
	v_cvt_pk_bf16_f32 v0, v0, v2
	s_nop 0
	v_lshlrev_b32_e32 v3, 16, v9
	v_lshlrev_b32_e32 v2, 16, v13
	v_and_b32_e32 v7, 0xffff0000, v9
	v_and_b32_e32 v6, 0xffff0000, v13
	s_waitcnt vmcnt(2)
	v_pk_mul_f32 v[8:9], v[236:237], v[2:3] op_sel:[0,1] op_sel_hi:[1,0]
	v_pk_mul_f32 v[12:13], v[238:239], v[6:7] op_sel:[0,1] op_sel_hi:[1,0]
	v_pk_mul_f32 v[6:7], v[238:239], v[6:7]
	v_pk_mul_f32 v[2:3], v[236:237], v[2:3]
	v_sub_f32_e32 v1, v8, v9
	v_add_f32_e32 v6, v7, v6
	v_add_f32_e32 v2, v3, v2
	v_sub_f32_e32 v3, v12, v13
	v_cvt_pk_bf16_f32 v5, v1, v3
	v_cvt_pk_bf16_f32 v1, v2, v6
	s_nop 0
	v_lshlrev_b32_e32 v3, 16, v10
	v_lshlrev_b32_e32 v2, 16, v14
	v_and_b32_e32 v13, 0xffff0000, v10
	v_and_b32_e32 v12, 0xffff0000, v14
	s_waitcnt vmcnt(1)
	v_pk_mul_f32 v[16:17], v[240:241], v[2:3] op_sel:[0,1] op_sel_hi:[1,0]
	v_pk_mul_f32 v[2:3], v[240:241], v[2:3]
	v_pk_mul_f32 v[6:7], v[242:243], v[12:13] op_sel:[0,1] op_sel_hi:[1,0]
	v_pk_mul_f32 v[8:9], v[242:243], v[12:13]
	v_add_f32_e32 v2, v3, v2
	v_sub_f32_e32 v10, v16, v17
	v_sub_f32_e32 v3, v6, v7
	v_add_f32_e32 v7, v9, v8
	v_cvt_pk_bf16_f32 v6, v10, v3
	v_cvt_pk_bf16_f32 v2, v2, v7
	s_nop 0
	v_add_u32_e32 v12, s73, v144
	v_add_u32_e32 v8, s73, v143
	v_ashrrev_i32_e32 v13, 31, v12
	v_ashrrev_i32_e32 v9, 31, v8
	v_lshlrev_b64 v[12:13], 7, v[12:13]
	v_and_b32_e32 v3, 0x78, v30
	v_add_u32_e32 v20, s73, v145
	v_lshlrev_b64 v[22:23], 13, v[8:9]
	v_lshl_add_u64 v[12:13], s[10:11], 0, v[12:13]
	v_lshlrev_b32_e32 v112, 1, v3
	v_ashrrev_i32_e32 v21, 31, v20
	v_lshl_add_u64 v[26:27], v[12:13], 0, v[114:115]
	v_lshl_add_u64 v[12:13], s[8:9], 0, v[22:23]
	v_lshlrev_b64 v[20:21], 13, v[20:21]
	v_lshl_add_u64 v[22:23], v[12:13], 0, v[112:113]
	v_lshlrev_b32_e32 v13, 16, v11
	v_lshlrev_b32_e32 v12, 16, v15
	v_and_b32_e32 v11, 0xffff0000, v11
	v_and_b32_e32 v10, 0xffff0000, v15
	v_lshl_add_u64 v[20:21], s[8:9], 0, v[20:21]
	v_lshl_add_u64 v[24:25], v[20:21], 0, v[112:113]
	v_bfe_u32 v30, v30, 5, 2
	s_waitcnt vmcnt(0)
	v_pk_mul_f32 v[14:15], v[244:245], v[12:13] op_sel:[0,1] op_sel_hi:[1,0]
	v_pk_mul_f32 v[12:13], v[244:245], v[12:13]
	v_pk_mul_f32 v[16:17], v[246:247], v[10:11] op_sel:[0,1] op_sel_hi:[1,0]
	v_pk_mul_f32 v[10:11], v[246:247], v[10:11]
	v_sub_f32_e32 v3, v14, v15
	v_sub_f32_e32 v7, v16, v17
	v_add_f32_e32 v10, v11, v10
	v_add_f32_e32 v9, v13, v12
	v_cvt_pk_bf16_f32 v7, v3, v7
	v_cvt_pk_bf16_f32 v3, v9, v10
	global_load_dwordx4 v[10:13], v[22:23], off offset:256
	global_load_dwordx4 v[14:17], v[24:25], off offset:256
	global_load_dwordx4 v[18:21], v[22:23], off
	s_nop 0
	global_load_dwordx4 v[22:25], v[24:25], off
	s_nop 0
	global_load_dwordx4 v[26:29], v[26:27], off
	v_and_b32_e32 v9, 0xfffff0, v143
	v_and_or_b32 v9, v32, 8, v9
	v_and_or_b32 v32, v33, 4, v34
	v_and_b32_e32 v33, 0xfffff0, v145
	v_lshlrev_b32_e32 v34, 1, v145
	v_lshrrev_b32_e32 v9, 1, v9
	v_and_or_b32 v33, v34, 8, v33
	v_or_b32_e32 v9, v9, v30
	v_lshrrev_b32_e32 v33, 1, v33
	v_lshlrev_b32_e32 v31, 6, v32
	v_and_b32_e32 v32, 48, v112
	v_lshlrev_b32_e32 v9, 9, v9
	v_or_b32_e32 v30, v33, v30
	v_or3_b32 v9, v9, v31, v32
	v_lshlrev_b32_e32 v30, 9, v30
	v_lshrrev_b32_e32 v34, 1, v119
	v_bitop3_b32 v34, v112, v34, s47 bitop3:0x78
	v_or3_b32 v30, v30, v31, v32
	v_add_u32_e32 v151, 0, v9
	ds_write_b128 v142, v[4:7] offset:6144
	ds_write_b128 v142, v[0:3] offset:7168
	v_add_u32_e32 v148, v35, v34
	v_add_u32_e32 v149, v38, v34
	v_add_u32_e32 v152, 0, v30
	s_waitcnt vmcnt(0)
	s_waitcnt vmcnt(4)
	ds_write_b128 v151, v[10:13]
	s_waitcnt vmcnt(3)
	ds_write_b128 v152, v[14:17]
	s_waitcnt vmcnt(2)
	ds_write_b128 v148, v[18:21] offset:32768
	s_waitcnt vmcnt(1)
	ds_write_b128 v149, v[22:25] offset:32768
	s_waitcnt vmcnt(0)
	ds_write_b128 v150, v[26:29] offset:32768
	s_waitcnt lgkmcnt(0)
	s_barrier
; template <int DQK>
; __device__ __forceinline__ void qkt(f32x16& p0, f32x16& p1, const char* Ks, const bf16x8* qr, const char* ql, int r32, int hi) {
;   p0 = f32x16{}; p1 = f32x16{};
; #pragma unroll
;   for (int d0 = 0; d0 < DQK / 16; ++d0) { const int cb = (d0 * 16 + hi * 8) * 2;
;     bf16x8 b0 = *reinterpret_cast<const bf16x8*>(Ks + r32 * (DQK * 2) + (cb ^ ((r32 & 7) << 4)));
;     bf16x8 b1 = *reinterpret_cast<const bf16x8*>(Ks + (32 + r32) * (DQK * 2) + (cb ^ ((r32 & 7) << 4)));
;     constexpr int NQR = DQK == 192 ? 4 : 8;
;     bf16x8 qv; if (d0 < NQR) qv = qr[d0 < NQR ? d0 : 0]; else qv = *reinterpret_cast<const bf16x8*>(ql + (d0 - NQR) * 1024);
;     p0 = __builtin_amdgcn_mfma_f32_32x32x16_bf16(b0, qv, p0, 0, 0, 0);
;     p1 = __builtin_amdgcn_mfma_f32_32x32x16_bf16(b1, qv, p1, 0, 0, 0); }
; }
	ds_read_b128 v[0:3], v147 offset:32768
	ds_read_b128 v[4:7], v147 offset:45056
	s_waitcnt lgkmcnt(1)
	v_mfma_f32_32x32x16_bf16 v[64:79], v[0:3], v[108:111], 0
	v_lshl_add_u32 v119, v123, 2, s42
	v_lshlrev_b32_e32 v123, 3, v120
	v_and_b32_e32 v127, 0x100, v123
	v_lshl_add_u32 v139, v138, 2, v119
	s_waitcnt lgkmcnt(0)
	v_mfma_f32_32x32x16_bf16 v[80:95], v[4:7], v[108:111], 0
	ds_read_b128 v[0:3], v153 offset:32768
	ds_read_b128 v[4:7], v153 offset:45056
	s_waitcnt lgkmcnt(1)
	v_mfma_f32_32x32x16_bf16 v[64:79], v[0:3], v[104:107], v[64:79]
	s_waitcnt lgkmcnt(0)
	v_mfma_f32_32x32x16_bf16 v[80:95], v[4:7], v[104:107], v[80:95]
	ds_read_b128 v[0:3], v154 offset:32768
	ds_read_b128 v[4:7], v154 offset:45056
	s_waitcnt lgkmcnt(1)
	v_mfma_f32_32x32x16_bf16 v[64:79], v[0:3], v[100:103], v[64:79]
	s_waitcnt lgkmcnt(0)
	v_mfma_f32_32x32x16_bf16 v[80:95], v[4:7], v[100:103], v[80:95]
	ds_read_b128 v[0:3], v155 offset:32768
	ds_read_b128 v[4:7], v155 offset:45056
	s_waitcnt lgkmcnt(1)
	v_mfma_f32_32x32x16_bf16 v[64:79], v[0:3], v[96:99], v[64:79]
	s_waitcnt lgkmcnt(0)
	v_mfma_f32_32x32x16_bf16 v[80:95], v[4:7], v[96:99], v[80:95]
	ds_read_b128 v[0:3], v156 offset:32768
	ds_read_b128 v[4:7], v142
	ds_read_b128 v[10:13], v156 offset:45056
	ds_read_b128 v[14:17], v142 offset:1024
	s_waitcnt lgkmcnt(2)
	v_mfma_f32_32x32x16_bf16 v[64:79], v[0:3], v[4:7], v[64:79]
	s_waitcnt lgkmcnt(1)
	v_mfma_f32_32x32x16_bf16 v[80:95], v[10:13], v[4:7], v[80:95]
	ds_read_b128 v[0:3], v160 offset:32768
	ds_read_b128 v[4:7], v160 offset:45056
	s_waitcnt lgkmcnt(1)
	v_mfma_f32_32x32x16_bf16 v[64:79], v[0:3], v[14:17], v[64:79]
	s_waitcnt lgkmcnt(0)
	v_mfma_f32_32x32x16_bf16 v[80:95], v[4:7], v[14:17], v[80:95]
	ds_read_b128 v[0:3], v159 offset:32768
	ds_read_b128 v[4:7], v142 offset:2048
	ds_read_b128 v[10:13], v159 offset:45056
	ds_read_b128 v[14:17], v142 offset:3072
	s_waitcnt lgkmcnt(2)
	v_mfma_f32_32x32x16_bf16 v[64:79], v[0:3], v[4:7], v[64:79]
	s_waitcnt lgkmcnt(1)
	v_mfma_f32_32x32x16_bf16 v[80:95], v[10:13], v[4:7], v[80:95]
	ds_read_b128 v[0:3], v162 offset:32768
	ds_read_b128 v[4:7], v162 offset:45056
	s_waitcnt lgkmcnt(1)
	v_mfma_f32_32x32x16_bf16 v[64:79], v[0:3], v[14:17], v[64:79]
	s_waitcnt lgkmcnt(0)
	v_mfma_f32_32x32x16_bf16 v[80:95], v[4:7], v[14:17], v[80:95]
	ds_read_b128 v[0:3], v163 offset:32768
	ds_read_b128 v[4:7], v142 offset:4096
	ds_read_b128 v[10:13], v163 offset:45056
	ds_read_b128 v[14:17], v142 offset:5120
	s_waitcnt lgkmcnt(2)
	v_mfma_f32_32x32x16_bf16 v[64:79], v[0:3], v[4:7], v[64:79]
	s_waitcnt lgkmcnt(1)
	v_mfma_f32_32x32x16_bf16 v[80:95], v[10:13], v[4:7], v[80:95]
	ds_read_b128 v[0:3], v166 offset:32768
	ds_read_b128 v[4:7], v166 offset:45056
	s_waitcnt lgkmcnt(1)
	v_mfma_f32_32x32x16_bf16 v[64:79], v[0:3], v[14:17], v[64:79]
	s_waitcnt lgkmcnt(0)
	v_mfma_f32_32x32x16_bf16 v[80:95], v[4:7], v[14:17], v[80:95]
	ds_read_b128 v[0:3], v165 offset:32768
	ds_read_b128 v[4:7], v142 offset:6144
	ds_read_b128 v[10:13], v165 offset:45056
	ds_read_b128 v[14:17], v142 offset:7168
	s_waitcnt lgkmcnt(2)
	v_mfma_f32_32x32x16_bf16 v[64:79], v[0:3], v[4:7], v[64:79]
	ds_read_b128 v[0:3], v168 offset:32768
	s_waitcnt lgkmcnt(2)
	v_mfma_f32_32x32x16_bf16 v[80:95], v[10:13], v[4:7], v[80:95]
	v_add_u32_e32 v4, 0x60, v8
	v_ashrrev_i32_e32 v5, 31, v4
	v_lshlrev_b64 v[8:9], 13, v[4:5]
	ds_read_b128 v[4:7], v168 offset:45056
	s_waitcnt lgkmcnt(1)
	v_mfma_f32_32x32x16_bf16 v[64:79], v[0:3], v[14:17], v[64:79]
	v_lshl_add_u64 v[0:1], s[8:9], 0, v[8:9]
	v_lshl_add_u64 v[0:1], v[0:1], 0, v[112:113]
	global_load_dwordx4 v[180:183], v[0:1], off offset:256
	global_load_dwordx4 v[186:189], v[0:1], off
	s_waitcnt lgkmcnt(0)
; #define SWAIT() asm volatile("s_waitcnt vmcnt(0)" ::: "memory")
; __device__ __forceinline__ void partialSM(f32x16& p0, f32x16& p1, float& m_reg, float& mn, float& alpha, const float C, const float THRS) {
;   float pmax = p0[0];
; #pragma unroll
;   for (int r = 1; r < 16; ++r) pmax = fmaxf(pmax, p0[r]);
; #pragma unroll
;   for (int r = 0; r < 16; ++r) pmax = fmaxf(pmax, p1[r]);
;   { auto rr = __builtin_amdgcn_permlane32_swap(__float_as_uint(pmax), __float_as_uint(pmax), false, false);
;     pmax = fmaxf(__uint_as_float(rr[0]), __uint_as_float(rr[1])); }
;   if (__builtin_expect(__all(pmax - m_reg <= THRS), 1)) { mn = m_reg; alpha = 1.f; }
;   else { mn = fmaxf(m_reg, pmax); alpha = __builtin_amdgcn_exp2f((m_reg - mn) * C); m_reg = mn; }
;   float mnC = -mn * C;
; #pragma unroll
;   for (int r = 0; r < 16; ++r) p0[r] = fmaf(p0[r], C, mnC);
; #pragma unroll
;   for (int r = 0; r < 16; ++r) p1[r] = fmaf(p1[r], C, mnC);
; #pragma unroll
;   for (int r = 0; r < 16; ++r) p0[r] = __builtin_amdgcn_exp2f(p0[r]);
; }
; template <int MODE>
; __device__ __forceinline__ void attn_body(const Job J, char* lds) {
;     ...
;   qkt<DQK>(pA0, pA1, K_lds, qr, ql, r32, hi); MASK(pA0, pA1, 0); partialSM(pA0, pA1, m_reg, mnA, alA, C, THRS);
;   SLOAD(1);
;   SWAIT(); SWRITE(1); __syncthreads();
	v_mfma_f32_32x32x16_bf16 v[80:95], v[4:7], v[14:17], v[80:95]
	s_nop 5
	v_max_f32_e32 v0, v65, v65
	v_max_f32_e32 v1, v64, v64
	v_max_f32_e32 v0, v1, v0
	v_max3_f32 v0, v0, v66, v67
	v_max3_f32 v0, v0, v68, v69
	v_max3_f32 v0, v0, v70, v71
	v_max3_f32 v0, v0, v72, v73
	v_max3_f32 v0, v0, v74, v75
	v_max3_f32 v0, v0, v76, v77
	v_max3_f32 v0, v0, v78, v79
	v_max3_f32 v0, v0, v80, v81
	v_max3_f32 v0, v0, v82, v83
	v_max3_f32 v0, v0, v84, v85
	v_max3_f32 v0, v0, v86, v87
	v_max3_f32 v0, v0, v88, v89
	v_max3_f32 v0, v0, v90, v91
	v_max3_f32 v0, v0, v92, v93
	v_max3_f32 v0, v0, v94, v95
	v_mov_b32_e32 v1, v0
	s_nop 1
	v_permlane32_swap_b32_e32 v0, v1
	v_max_f32_e32 v1, v1, v1
	v_max_f32_e32 v0, v0, v0
	v_max_f32_e32 v0, v0, v1
	v_add_f32_e32 v1, 0x7149f2ca, v0
	v_cmp_ge_f32_e32 vcc, s56, v1
	s_cmp_eq_u64 vcc, exec
	s_cselect_b64 vcc, -1, 0
	s_or_b32 s6, s73, 64
	v_max_f32_e32 v124, 0xf149f2ca, v0
	v_add_u32_e32 v0, s6, v143
	v_ashrrev_i32_e32 v1, 31, v0
	v_lshlrev_b64 v[0:1], 13, v[0:1]
	v_lshl_add_u64 v[0:1], s[8:9], 0, v[0:1]
	v_add_u32_e32 v2, s6, v144
	v_lshl_add_u64 v[0:1], v[0:1], 0, v[112:113]
	v_ashrrev_i32_e32 v3, 31, v2
	global_load_dwordx4 v[190:193], v[0:1], off offset:256
	global_load_dwordx4 v[214:217], v[0:1], off
	v_lshlrev_b64 v[2:3], 7, v[2:3]
	v_lshl_add_u64 v[2:3], s[10:11], 0, v[2:3]
	v_lshl_add_u64 v[0:1], v[2:3], 0, v[114:115]
	global_load_dwordx4 v[218:221], v[0:1], off
	v_cndmask_b32_e32 v184, v124, v136, vcc
	v_cmp_gt_u32_e64 s[6:7], 32, v120
	v_lshl_add_u64 v[120:121], s[10:11], 0, v[114:115]
	v_and_or_b32 v114, v123, 24, v126
	v_lshl_add_u64 v[122:123], s[8:9], 0, v[112:113]
	v_sub_f32_e32 v112, 0xf149f2ca, v124
	v_mul_f32_e32 v130, 0xbdd53b94, v184
	v_mul_f32_e32 v112, 0x3dd53b94, v112
	v_mov_b32_e32 v185, v130
	v_exp_f32_e32 v141, v112
	v_fmamk_f32 v64, v64, 0x3dd53b94, v130
	v_fmamk_f32 v65, v65, 0x3dd53b94, v130
	v_fmamk_f32 v66, v66, 0x3dd53b94, v130
	v_fmamk_f32 v67, v67, 0x3dd53b94, v130
	v_fmamk_f32 v68, v68, 0x3dd53b94, v130
	v_fmamk_f32 v69, v69, 0x3dd53b94, v130
	v_fmamk_f32 v70, v70, 0x3dd53b94, v130
	v_fmamk_f32 v71, v71, 0x3dd53b94, v130
	v_fmamk_f32 v72, v72, 0x3dd53b94, v130
	v_fmamk_f32 v73, v73, 0x3dd53b94, v130
	v_fmamk_f32 v74, v74, 0x3dd53b94, v130
	v_fmamk_f32 v75, v75, 0x3dd53b94, v130
	v_fmamk_f32 v76, v76, 0x3dd53b94, v130
	v_fmamk_f32 v77, v77, 0x3dd53b94, v130
	v_fmamk_f32 v78, v78, 0x3dd53b94, v130
	v_fmac_f32_e32 v185, 0x3dd53b94, v79
	v_mov_b64_e32 v[0:1], s[12:13]
	v_exp_f32_e32 v210, v64
	v_exp_f32_e32 v212, v65
	v_exp_f32_e32 v208, v66
	v_exp_f32_e32 v211, v67
	v_exp_f32_e32 v207, v68
	v_exp_f32_e32 v209, v69
	v_exp_f32_e32 v205, v70
	v_exp_f32_e32 v206, v71
	v_exp_f32_e32 v202, v72
	v_exp_f32_e32 v204, v73
	v_exp_f32_e32 v201, v74
	v_exp_f32_e32 v203, v75
	v_exp_f32_e32 v198, v76
	v_exp_f32_e32 v200, v77
	v_exp_f32_e32 v197, v78
	v_exp_f32_e32 v199, v185
	v_mov_b64_e32 v[14:15], s[26:27]
	v_or3_b32 v114, v114, v125, v127
	s_waitcnt vmcnt(0)
	v_mov_b64_e32 v[2:3], s[14:15]
	v_mov_b64_e32 v[4:5], s[16:17]
	v_mov_b64_e32 v[6:7], s[18:19]
	v_mov_b64_e32 v[8:9], s[20:21]
	v_mov_b64_e32 v[10:11], s[22:23]
	v_mov_b64_e32 v[12:13], s[24:25]
	v_mov_b64_e32 v[62:63], v[14:15]
	v_mov_b64_e32 v[46:47], v[14:15]
	v_mov_b64_e32 v[30:31], v[14:15]
	v_add_u32_e32 v157, s38, v114
	s_addk_i32 s38, 0x4000
	v_mov_b64_e32 v[60:61], v[12:13]
	v_mov_b64_e32 v[58:59], v[10:11]
	v_mov_b64_e32 v[56:57], v[8:9]
	v_mov_b64_e32 v[54:55], v[6:7]
	v_mov_b64_e32 v[52:53], v[4:5]
	v_mov_b64_e32 v[50:51], v[2:3]
	v_mov_b64_e32 v[48:49], v[0:1]
	v_mov_b64_e32 v[44:45], v[12:13]
	v_mov_b64_e32 v[42:43], v[10:11]
	v_mov_b64_e32 v[40:41], v[8:9]
	v_mov_b64_e32 v[38:39], v[6:7]
	v_mov_b64_e32 v[36:37], v[4:5]
	v_mov_b64_e32 v[34:35], v[2:3]
	v_mov_b64_e32 v[32:33], v[0:1]
	v_mov_b64_e32 v[28:29], v[12:13]
	v_mov_b64_e32 v[26:27], v[10:11]
	v_mov_b64_e32 v[24:25], v[8:9]
	v_mov_b64_e32 v[22:23], v[6:7]
	v_mov_b64_e32 v[20:21], v[4:5]
	v_mov_b64_e32 v[18:19], v[2:3]
	v_mov_b64_e32 v[16:17], v[0:1]
	v_add_u32_e32 v140, s38, v114
	v_pk_fma_f32 v[126:127], v[94:95], s[34:35], v[130:131] op_sel_hi:[1,0,0]
	v_pk_fma_f32 v[132:133], v[92:93], s[34:35], v[130:131] op_sel_hi:[1,0,0]
	v_pk_fma_f32 v[134:135], v[90:91], s[34:35], v[130:131] op_sel_hi:[1,0,0]
	v_pk_fma_f32 v[112:113], v[88:89], s[34:35], v[130:131] op_sel_hi:[1,0,0]
	v_pk_fma_f32 v[114:115], v[86:87], s[34:35], v[130:131] op_sel_hi:[1,0,0]
	v_pk_fma_f32 v[124:125], v[84:85], s[34:35], v[130:131] op_sel_hi:[1,0,0]
	v_pk_fma_f32 v[128:129], v[82:83], s[34:35], v[130:131] op_sel_hi:[1,0,0]
	v_pk_fma_f32 v[130:131], v[80:81], s[34:35], v[130:131] op_sel_hi:[1,0,0]
	v_cndmask_b32_e64 v179, v141, 1.0, vcc
	v_mov_b32_e32 v141, 0
	s_waitcnt vmcnt(2)
	ds_write_b128 v151, v[190:193] offset:16384
	ds_write_b128 v152, v[180:183] offset:16384
	s_waitcnt vmcnt(1)
	ds_write_b128 v148, v[214:217] offset:57344
	ds_write_b128 v149, v[186:189] offset:57344
	s_waitcnt vmcnt(0)
	ds_write_b128 v150, v[218:221] offset:57344
	s_waitcnt lgkmcnt(0)
	s_barrier
